# attention: next-tile addresses computed before the wait on the current loads; v_cmp->v_cndmask spacing restored (on top of v87)
# baseline (speedup 1.0000x reference)
.LBB0_503:
	s_or_b64 exec, exec, s[54:55]
	s_lshl_b32 s3, s98, 5
	s_ashr_i32 s54, s3, 31
	s_add_u32 s12, s3, s12
	v_and_b32_e32 v186, 31, v154
	s_addc_u32 s54, s54, 0
	s_waitcnt vmcnt(8)
	v_or_b32_e32 v156, s12, v186
	v_mov_b32_e32 v157, s54
	s_add_u32 s54, s85, s57
	v_lshlrev_b64 v[2:3], 14, v[156:157]
	v_lshrrev_b32_e32 v121, 5, v185
	s_addc_u32 s55, s86, 0
	s_add_i32 s33, s33, -16
	v_lshl_add_u64 v[2:3], s[10:11], 0, v[2:3]
	s_add_u32 vcc_lo, s10, s14
	v_lshlrev_b32_e32 v187, 4, v154
	v_lshl_add_u64 v[2:3], v[2:3], 0, s[14:15]
	v_lshlrev_b32_e32 v162, 4, v121
	v_mov_b32_e32 v163, v129
	s_addc_u32 vcc_hi, s11, 0
	v_and_b32_e32 v128, 0xf0, v187
	v_lshl_add_u64 v[2:3], v[2:3], 0, v[162:163]
	v_lshl_add_u64 v[160:161], vcc, 0, v[128:129]
	v_ashrrev_i32_e32 v119, 4, v154
	v_lshl_add_u64 v[52:53], v[2:3], 0, s[36:37]
	v_add_co_u32_e32 v2, vcc, s65, v2
	v_add_u32_e32 v1, s56, v119
	s_nop 0
	v_addc_co_u32_e32 v3, vcc, 0, v3, vcc
	v_mov_b32_e32 v6, s33
	v_cmp_lt_i32_e32 vcc, 15, v1
	v_min_i32_e32 v0, 0x80f, v1
	global_load_dwordx4 v[80:83], v[2:3], off
	global_load_dwordx4 v[86:89], v[52:53], off offset:224
	v_cndmask_b32_e32 v1, v179, v6, vcc
	v_add_u32_e32 v2, v1, v0
	v_ashrrev_i32_e32 v3, 31, v2
	v_lshlrev_b64 v[2:3], 14, v[2:3]
	v_lshl_add_u64 v[2:3], v[160:161], 0, v[2:3]
	v_add_co_u32_e32 v4, vcc, s65, v2
	v_ashrrev_i32_e32 v1, 31, v0
	s_nop 0
	v_addc_co_u32_e32 v5, vcc, 0, v3, vcc
	v_add_co_u32_e32 v2, vcc, s63, v2
	v_lshl_add_u64 v[0:1], v[0:1], 2, s[54:55]
	s_nop 0
	v_addc_co_u32_e32 v3, vcc, 0, v3, vcc
	global_load_dwordx4 v[96:99], v[52:53], off offset:160
	global_load_dwordx4 v[100:103], v[52:53], off offset:192
	global_load_dwordx4 v[12:15], v[4:5], off offset:2048
	global_load_dwordx4 v[8:11], v[2:3], off
	v_add_u32_e32 v2, 0x200, v154
	v_ashrrev_i32_e32 v189, 4, v2
	v_add_u32_e32 v3, s56, v189
	v_cmp_lt_i32_e32 vcc, 15, v3
	v_min_i32_e32 v2, 0x80f, v3
	v_mul_lo_u32 v48, v48, s66
	v_cndmask_b32_e32 v3, v179, v6, vcc
	v_add_u32_e32 v4, v3, v2
	v_ashrrev_i32_e32 v5, 31, v4
	v_lshlrev_b64 v[4:5], 14, v[4:5]
	v_lshl_add_u64 v[54:55], v[160:161], 0, v[4:5]
	v_add_co_u32_e32 v4, vcc, s65, v54
	v_ashrrev_i32_e32 v3, 31, v2
	s_nop 0
	v_addc_co_u32_e32 v5, vcc, 0, v55, vcc
	global_load_dword v120, v[0:1], off
	s_nop 0
	global_load_dwordx4 v[4:7], v[4:5], off offset:2048
	v_add_co_u32_e32 v0, vcc, s63, v54
	v_add3_u32 v48, s67, v48, v50
	s_nop 0
	v_addc_co_u32_e32 v1, vcc, 0, v55, vcc
	v_lshl_add_u64 v[54:55], v[2:3], 2, s[54:55]
	global_load_dwordx4 v[0:3], v[0:1], off
	s_nop 0
	global_load_dword v118, v[54:55], off
	global_load_dwordx4 v[172:175], v[52:53], off offset:32
	global_load_dwordx4 v[164:167], v[52:53], off offset:64
	global_load_dwordx4 v[148:151], v[52:53], off offset:96
	global_load_dwordx4 v[140:143], v[52:53], off offset:128
	s_waitcnt vmcnt(19)
	ds_write2_b64 v48, v[36:37], v[38:39] offset1:1
	ds_write2_b64 v48, v[32:33], v[34:35] offset0:2 offset1:3
	ds_write2_b64 v48, v[24:25], v[26:27] offset0:4 offset1:5
	s_waitcnt vmcnt(15)
	ds_write2_b64 v48, v[44:45], v[46:47] offset0:6 offset1:7
	s_waitcnt vmcnt(14)
	ds_write2_b64 v48, v[40:41], v[42:43] offset0:8 offset1:9
	ds_write2_b64 v48, v[28:29], v[30:31] offset0:10 offset1:11
	ds_write2_b64 v48, v[20:21], v[22:23] offset0:12 offset1:13
	ds_write2_b64 v48, v[16:17], v[18:19] offset0:14 offset1:15
	v_and_b32_e32 v16, 32, v185
	v_add_u32_e32 v16, 0, v16
	v_add_u32_e32 v16, 0x25e00, v16
	ds_read_b128 v[76:79], v16
	ds_read_b128 v[72:75], v16 offset:16
	ds_read_b128 v[68:71], v16 offset:64
	ds_read_b128 v[64:67], v16 offset:80
	ds_read_b128 v[60:63], v16 offset:128
	ds_read_b128 v[56:59], v16 offset:144
	ds_read_b128 v[52:55], v16 offset:192
	ds_read_b128 v[48:51], v16 offset:208
	ds_read_b128 v[44:47], v16 offset:256
	ds_read_b128 v[40:43], v16 offset:272
	ds_read_b128 v[36:39], v16 offset:320
	ds_read_b128 v[32:35], v16 offset:336
	ds_read_b128 v[28:31], v16 offset:384
	ds_read_b128 v[24:27], v16 offset:400
	ds_read_b128 v[20:23], v16 offset:448
	ds_read_b128 v[16:19], v16 offset:464
	s_waitcnt vmcnt(13)
	v_and_b32_e32 v177, 0xffff0000, v80
	s_waitcnt vmcnt(12)
	v_and_b32_e32 v85, 0xffff0000, v89
	v_lshlrev_b32_e32 v122, 16, v89
	v_lshlrev_b32_e32 v110, 16, v88
	v_and_b32_e32 v89, 0xffff0000, v88
	v_mov_b32_e32 v88, v85
	v_and_b32_e32 v93, 0xffff0000, v87
	v_mov_b32_e32 v123, v110
	v_pk_mul_f32 v[90:91], v[88:89], v[88:89]
	v_lshlrev_b32_e32 v124, 16, v87
	v_lshlrev_b32_e32 v108, 16, v86
	v_and_b32_e32 v87, 0xffff0000, v86
	v_mov_b32_e32 v86, v93
	v_pk_fma_f32 v[190:191], v[122:123], v[122:123], v[90:91]
	v_mov_b32_e32 v125, v108
	v_pk_mul_f32 v[90:91], v[86:87], v[86:87]
	s_waitcnt vmcnt(10)
	v_and_b32_e32 v131, 0xffff0000, v101
	v_pk_fma_f32 v[192:193], v[124:125], v[124:125], v[90:91]
	v_and_b32_e32 v91, 0xffff0000, v103
	v_lshlrev_b32_e32 v106, 16, v102
	v_and_b32_e32 v95, 0xffff0000, v102
	v_mov_b32_e32 v94, v91
	v_lshlrev_b32_e32 v130, 16, v101
	v_mul_f32_e32 v84, v131, v131
	v_and_b32_e32 v105, 0xffff0000, v100
	v_lshlrev_b32_e32 v126, 16, v103
	v_mov_b32_e32 v127, v106
	v_pk_mul_f32 v[102:103], v[94:95], v[94:95]
	v_pk_fma_f32 v[196:197], v[130:131], v[130:131], v[84:85] op_sel_hi:[1,1,0]
	v_lshlrev_b32_e32 v104, 16, v100
	v_mul_f32_e32 v84, v105, v105
	v_and_b32_e32 v133, 0xffff0000, v99
	v_pk_fma_f32 v[194:195], v[126:127], v[126:127], v[102:103]
	v_pk_fma_f32 v[198:199], v[104:105], v[104:105], v[84:85] op_sel_hi:[1,1,0]
	v_lshlrev_b32_e32 v132, 16, v99
	v_mul_f32_e32 v84, v133, v133
	v_and_b32_e32 v103, 0xffff0000, v98
	v_pk_fma_f32 v[200:201], v[132:133], v[132:133], v[84:85] op_sel_hi:[1,1,0]
	v_lshlrev_b32_e32 v102, 16, v98
	v_mul_f32_e32 v84, v103, v103
	v_and_b32_e32 v135, 0xffff0000, v97
	v_pk_fma_f32 v[202:203], v[102:103], v[102:103], v[84:85] op_sel_hi:[1,1,0]
	v_lshlrev_b32_e32 v134, 16, v97
	v_mul_f32_e32 v84, v135, v135
	v_and_b32_e32 v101, 0xffff0000, v96
	v_pk_fma_f32 v[204:205], v[134:135], v[134:135], v[84:85] op_sel_hi:[1,1,0]
	v_lshlrev_b32_e32 v100, 16, v96
	v_mul_f32_e32 v84, v101, v101
	s_waitcnt vmcnt(0)
	v_and_b32_e32 v137, 0xffff0000, v143
	v_pk_fma_f32 v[206:207], v[100:101], v[100:101], v[84:85] op_sel_hi:[1,1,0]
	v_lshlrev_b32_e32 v136, 16, v143
	v_mul_f32_e32 v84, v137, v137
	v_and_b32_e32 v99, 0xffff0000, v142
	v_pk_fma_f32 v[208:209], v[136:137], v[136:137], v[84:85] op_sel_hi:[1,1,0]
	v_lshlrev_b32_e32 v98, 16, v142
	v_mul_f32_e32 v84, v99, v99
	v_and_b32_e32 v139, 0xffff0000, v141
	v_pk_fma_f32 v[210:211], v[98:99], v[98:99], v[84:85] op_sel_hi:[1,1,0]
	v_lshlrev_b32_e32 v138, 16, v141
	v_mul_f32_e32 v84, v139, v139
	v_and_b32_e32 v97, 0xffff0000, v140
	v_pk_fma_f32 v[212:213], v[138:139], v[138:139], v[84:85] op_sel_hi:[1,1,0]
	v_lshlrev_b32_e32 v96, 16, v140
	v_mul_f32_e32 v84, v97, v97
	v_and_b32_e32 v141, 0xffff0000, v151
	v_pk_fma_f32 v[214:215], v[96:97], v[96:97], v[84:85] op_sel_hi:[1,1,0]
	v_lshlrev_b32_e32 v140, 16, v151
	v_mul_f32_e32 v84, v141, v141
	v_and_b32_e32 v143, 0xffff0000, v150
	v_pk_fma_f32 v[216:217], v[140:141], v[140:141], v[84:85] op_sel_hi:[1,1,0]
	v_lshlrev_b32_e32 v142, 16, v150
	v_mul_f32_e32 v84, v143, v143
	v_and_b32_e32 v145, 0xffff0000, v149
	v_pk_fma_f32 v[218:219], v[142:143], v[142:143], v[84:85] op_sel_hi:[1,1,0]
	v_lshlrev_b32_e32 v144, 16, v149
	v_mul_f32_e32 v84, v145, v145
	v_and_b32_e32 v147, 0xffff0000, v148
	v_pk_fma_f32 v[220:221], v[144:145], v[144:145], v[84:85] op_sel_hi:[1,1,0]
	v_lshlrev_b32_e32 v146, 16, v148
	v_mul_f32_e32 v84, v147, v147
	v_and_b32_e32 v149, 0xffff0000, v167
	v_pk_fma_f32 v[222:223], v[146:147], v[146:147], v[84:85] op_sel_hi:[1,1,0]
	v_lshlrev_b32_e32 v148, 16, v167
	v_mul_f32_e32 v84, v149, v149
	v_and_b32_e32 v151, 0xffff0000, v166
	v_pk_fma_f32 v[224:225], v[148:149], v[148:149], v[84:85] op_sel_hi:[1,1,0]
	v_lshlrev_b32_e32 v150, 16, v166
	v_mul_f32_e32 v84, v151, v151
	v_and_b32_e32 v153, 0xffff0000, v165
	v_pk_fma_f32 v[226:227], v[150:151], v[150:151], v[84:85] op_sel_hi:[1,1,0]
	v_lshlrev_b32_e32 v152, 16, v165
	v_mul_f32_e32 v84, v153, v153
	v_and_b32_e32 v159, 0xffff0000, v164
	v_pk_fma_f32 v[228:229], v[152:153], v[152:153], v[84:85] op_sel_hi:[1,1,0]
	v_lshlrev_b32_e32 v158, 16, v164
	v_mul_f32_e32 v84, v159, v159
	v_and_b32_e32 v165, 0xffff0000, v175
	v_pk_fma_f32 v[230:231], v[158:159], v[158:159], v[84:85] op_sel_hi:[1,1,0]
	v_lshlrev_b32_e32 v164, 16, v175
	v_mul_f32_e32 v84, v165, v165
	v_and_b32_e32 v167, 0xffff0000, v174
	v_pk_fma_f32 v[232:233], v[164:165], v[164:165], v[84:85] op_sel_hi:[1,1,0]
	v_lshlrev_b32_e32 v166, 16, v174
	v_mul_f32_e32 v84, v167, v167
	v_and_b32_e32 v169, 0xffff0000, v173
	v_pk_fma_f32 v[234:235], v[166:167], v[166:167], v[84:85] op_sel_hi:[1,1,0]
	v_lshlrev_b32_e32 v168, 16, v173
	v_mul_f32_e32 v84, v169, v169
	v_and_b32_e32 v171, 0xffff0000, v172
	v_and_b32_e32 v175, 0xffff0000, v82
	v_pk_fma_f32 v[236:237], v[168:169], v[168:169], v[84:85] op_sel_hi:[1,1,0]
	v_lshlrev_b32_e32 v170, 16, v172
	v_mul_f32_e32 v84, v171, v171
	v_and_b32_e32 v173, 0xffff0000, v83
	v_lshlrev_b32_e32 v174, 16, v82
	v_mul_f32_e32 v82, v175, v175
	v_pk_fma_f32 v[238:239], v[170:171], v[170:171], v[84:85] op_sel_hi:[1,1,0]
	v_lshlrev_b32_e32 v172, 16, v83
	v_mul_f32_e32 v84, v173, v173
	v_pk_fma_f32 v[242:243], v[174:175], v[174:175], v[82:83] op_sel_hi:[1,1,0]
	v_and_b32_e32 v83, 0xffff0000, v81
	v_pk_fma_f32 v[240:241], v[172:173], v[172:173], v[84:85] op_sel_hi:[1,1,0]
	v_lshlrev_b32_e32 v82, 16, v81
	v_mul_f32_e32 v84, v83, v83
	v_lshlrev_b32_e32 v176, 16, v80
	v_mul_f32_e32 v80, v177, v177
	v_pk_fma_f32 v[244:245], v[82:83], v[82:83], v[84:85] op_sel_hi:[1,1,0]
	v_pk_fma_f32 v[80:81], v[176:177], v[176:177], v[80:81] op_sel_hi:[1,1,0]
	s_nop 0
	v_pk_add_f32 v[80:81], v[80:81], v[244:245]
	s_nop 0
	v_pk_add_f32 v[80:81], v[242:243], v[80:81]
	s_nop 0
	v_pk_add_f32 v[80:81], v[240:241], v[80:81]
	s_nop 0
	v_pk_add_f32 v[80:81], v[238:239], v[80:81]
	s_nop 0
	v_pk_add_f32 v[80:81], v[236:237], v[80:81]
	s_nop 0
	v_pk_add_f32 v[80:81], v[234:235], v[80:81]
	s_nop 0
	v_pk_add_f32 v[80:81], v[232:233], v[80:81]
	s_nop 0
	v_pk_add_f32 v[80:81], v[230:231], v[80:81]
	s_nop 0
	v_pk_add_f32 v[80:81], v[228:229], v[80:81]
	s_nop 0
	v_pk_add_f32 v[80:81], v[226:227], v[80:81]
	s_nop 0
	v_pk_add_f32 v[80:81], v[224:225], v[80:81]
	s_nop 0
	v_pk_add_f32 v[80:81], v[222:223], v[80:81]
	s_nop 0
	v_pk_add_f32 v[80:81], v[220:221], v[80:81]
	s_nop 0
	v_pk_add_f32 v[80:81], v[218:219], v[80:81]
	s_nop 0
	v_pk_add_f32 v[80:81], v[216:217], v[80:81]
	s_nop 0
	v_pk_add_f32 v[80:81], v[214:215], v[80:81]
	s_nop 0
	v_pk_add_f32 v[80:81], v[212:213], v[80:81]
	s_nop 0
	v_pk_add_f32 v[80:81], v[210:211], v[80:81]
	s_nop 0
	v_pk_add_f32 v[80:81], v[208:209], v[80:81]
	s_nop 0
	v_pk_add_f32 v[80:81], v[206:207], v[80:81]
	s_nop 0
	v_pk_add_f32 v[80:81], v[204:205], v[80:81]
	s_nop 0
	v_pk_add_f32 v[80:81], v[202:203], v[80:81]
	s_nop 0
	v_pk_add_f32 v[80:81], v[200:201], v[80:81]
	s_nop 0
	v_pk_add_f32 v[80:81], v[198:199], v[80:81]
	s_nop 0
	v_pk_add_f32 v[80:81], v[196:197], v[80:81]
	s_nop 0
	v_pk_add_f32 v[80:81], v[194:195], v[80:81] op_sel:[1,0] op_sel_hi:[0,1]
	v_pk_add_f32 v[80:81], v[194:195], v[80:81]
	s_nop 0
	v_pk_add_f32 v[80:81], v[192:193], v[80:81] op_sel:[1,0] op_sel_hi:[0,1]
	v_pk_add_f32 v[80:81], v[192:193], v[80:81]
	s_nop 0
	v_pk_add_f32 v[80:81], v[190:191], v[80:81] op_sel:[1,0] op_sel_hi:[0,1]
	v_pk_add_f32 v[80:81], v[190:191], v[80:81]
	s_nop 0
	v_mov_b32_e32 v81, v80
	s_nop 1
	v_permlane32_swap_b32_e32 v80, v81
	s_and_saveexec_b64 s[56:57], s[0:1]
	v_add_u32_e32 v84, 0, v187
	ds_write_b128 v84, v[112:115] offset:34816
	s_or_b64 exec, exec, s[56:57]
	v_add_f32_e32 v80, v80, v81
	v_fmamk_f32 v80, v80, 0x3c000000, v178
	v_mul_f32_e32 v81, 0x4b800000, v80
	v_cmp_gt_f32_e32 vcc, s68, v80
	v_mov_b32_e32 v123, v85
	v_mov_b32_e32 v109, v87
	v_cndmask_b32_e32 v80, v80, v81, vcc
	v_rsq_f32_e32 v80, v80
	v_mov_b32_e32 v111, v89
	v_mov_b32_e32 v127, v91
	v_mov_b32_e32 v125, v93
	v_mul_f32_e32 v81, 0x45800000, v80
	v_cndmask_b32_e32 v188, v80, v81, vcc
	v_pk_mul_f32 v[80:81], v[188:189], v[176:177] op_sel_hi:[0,1]
	s_waitcnt lgkmcnt(14)
	v_pk_mul_f32 v[76:77], v[76:77], v[80:81]
	v_mov_b32_e32 v107, v95
	v_cvt_pk_bf16_f32 v80, v76, v77
	v_pk_mul_f32 v[76:77], v[188:189], v[82:83] op_sel_hi:[0,1]
	v_pk_mul_f32 v[76:77], v[78:79], v[76:77]
	s_add_i32 s82, s3, s59
	v_cvt_pk_bf16_f32 v81, v76, v77
	v_pk_mul_f32 v[76:77], v[188:189], v[174:175] op_sel_hi:[0,1]
	v_pk_mul_f32 v[72:73], v[72:73], v[76:77]
	v_mul_lo_u32 v174, v119, s69
	v_cvt_pk_bf16_f32 v82, v72, v73
	v_pk_mul_f32 v[72:73], v[188:189], v[172:173] op_sel_hi:[0,1]
	v_pk_mul_f32 v[72:73], v[74:75], v[72:73]
	v_mul_lo_u32 v175, v189, s69
	v_cvt_pk_bf16_f32 v83, v72, v73
	v_pk_mul_f32 v[72:73], v[188:189], v[170:171] op_sel_hi:[0,1]
	s_waitcnt lgkmcnt(13)
	v_pk_mul_f32 v[68:69], v[68:69], v[72:73]
	s_add_i32 s15, s82, 16
	v_cvt_pk_bf16_f32 v84, v68, v69
	v_pk_mul_f32 v[68:69], v[188:189], v[168:169] op_sel_hi:[0,1]
	v_pk_mul_f32 v[68:69], v[70:71], v[68:69]
	v_lshlrev_b32_e32 v163, 3, v121
	v_cvt_pk_bf16_f32 v85, v68, v69
	v_pk_mul_f32 v[68:69], v[188:189], v[166:167] op_sel_hi:[0,1]
	s_waitcnt lgkmcnt(12)
	v_pk_mul_f32 v[64:65], v[64:65], v[68:69]
	s_add_i32 s82, s82, 47
	v_cvt_pk_bf16_f32 v86, v64, v65
	v_pk_mul_f32 v[64:65], v[188:189], v[164:165] op_sel_hi:[0,1]
	v_pk_mul_f32 v[64:65], v[66:67], v[64:65]
	s_mov_b32 s64, 1
	v_cvt_pk_bf16_f32 v87, v64, v65
	v_pk_mul_f32 v[64:65], v[188:189], v[158:159] op_sel_hi:[0,1]
	s_waitcnt lgkmcnt(11)
	v_pk_mul_f32 v[60:61], v[60:61], v[64:65]
	v_lshlrev_b32_e32 v159, 2, v121
	v_cvt_pk_bf16_f32 v88, v60, v61
	v_pk_mul_f32 v[60:61], v[188:189], v[152:153] op_sel_hi:[0,1]
	v_pk_mul_f32 v[60:61], v[62:63], v[60:61]
	v_add_u32_e32 v158, s15, v186
	v_cvt_pk_bf16_f32 v89, v60, v61
	v_pk_mul_f32 v[60:61], v[188:189], v[150:151] op_sel_hi:[0,1]
	s_waitcnt lgkmcnt(10)
	v_pk_mul_f32 v[56:57], v[56:57], v[60:61]
	v_mov_b32_e32 v60, v129
	v_cvt_pk_bf16_f32 v90, v56, v57
	v_pk_mul_f32 v[56:57], v[188:189], v[148:149] op_sel_hi:[0,1]
	v_pk_mul_f32 v[56:57], v[58:59], v[56:57]
	v_mov_b32_e32 v58, v129
	v_cvt_pk_bf16_f32 v91, v56, v57
	v_pk_mul_f32 v[56:57], v[188:189], v[146:147] op_sel_hi:[0,1]
	s_waitcnt lgkmcnt(9)
	v_pk_mul_f32 v[52:53], v[52:53], v[56:57]
	v_mov_b32_e32 v56, v129
	v_cvt_pk_bf16_f32 v92, v52, v53
	v_pk_mul_f32 v[52:53], v[188:189], v[144:145] op_sel_hi:[0,1]
	v_pk_mul_f32 v[52:53], v[54:55], v[52:53]
	v_mov_b32_e32 v54, v129
	v_cvt_pk_bf16_f32 v93, v52, v53
	v_pk_mul_f32 v[52:53], v[188:189], v[142:143] op_sel_hi:[0,1]
	s_waitcnt lgkmcnt(8)
	v_pk_mul_f32 v[48:49], v[48:49], v[52:53]
	v_mov_b32_e32 v52, v129
	v_cvt_pk_bf16_f32 v94, v48, v49
	v_pk_mul_f32 v[48:49], v[188:189], v[140:141] op_sel_hi:[0,1]
	v_pk_mul_f32 v[48:49], v[50:51], v[48:49]
	v_mov_b32_e32 v50, v129
	v_cvt_pk_bf16_f32 v95, v48, v49
	v_pk_mul_f32 v[48:49], v[188:189], v[96:97] op_sel_hi:[0,1]
	s_waitcnt lgkmcnt(7)
	v_pk_mul_f32 v[44:45], v[44:45], v[48:49]
	v_mov_b32_e32 v48, v129
	v_cvt_pk_bf16_f32 v96, v44, v45
	v_pk_mul_f32 v[44:45], v[188:189], v[138:139] op_sel_hi:[0,1]
	v_pk_mul_f32 v[44:45], v[46:47], v[44:45]
	v_mov_b32_e32 v49, v129
	v_cvt_pk_bf16_f32 v97, v44, v45
	v_pk_mul_f32 v[44:45], v[188:189], v[98:99] op_sel_hi:[0,1]
	s_waitcnt lgkmcnt(6)
	v_pk_mul_f32 v[40:41], v[40:41], v[44:45]
	v_mov_b32_e32 v51, v129
	v_cvt_pk_bf16_f32 v98, v40, v41
	v_pk_mul_f32 v[40:41], v[188:189], v[136:137] op_sel_hi:[0,1]
	v_pk_mul_f32 v[40:41], v[42:43], v[40:41]
	v_mov_b32_e32 v53, v129
	v_cvt_pk_bf16_f32 v99, v40, v41
	v_pk_mul_f32 v[40:41], v[188:189], v[100:101] op_sel_hi:[0,1]
	s_waitcnt lgkmcnt(5)
	v_pk_mul_f32 v[36:37], v[40:41], v[36:37]
	v_mov_b32_e32 v55, v129
	v_cvt_pk_bf16_f32 v100, v36, v37
	v_pk_mul_f32 v[36:37], v[188:189], v[134:135] op_sel_hi:[0,1]
	v_pk_mul_f32 v[36:37], v[36:37], v[38:39]
	v_mov_b32_e32 v57, v129
	v_cvt_pk_bf16_f32 v101, v36, v37
	v_pk_mul_f32 v[36:37], v[188:189], v[102:103] op_sel_hi:[0,1]
	s_waitcnt lgkmcnt(4)
	v_pk_mul_f32 v[32:33], v[36:37], v[32:33]
	v_mov_b32_e32 v59, v129
	v_cvt_pk_bf16_f32 v102, v32, v33
	v_pk_mul_f32 v[32:33], v[188:189], v[132:133] op_sel_hi:[0,1]
	v_pk_mul_f32 v[32:33], v[32:33], v[34:35]
	v_mov_b32_e32 v61, v129
	v_cvt_pk_bf16_f32 v103, v32, v33
	v_pk_mul_f32 v[32:33], v[188:189], v[104:105] op_sel_hi:[0,1]
	s_waitcnt lgkmcnt(3)
	v_pk_mul_f32 v[28:29], v[32:33], v[28:29]
	v_mov_b32_e32 v62, v129
	v_cvt_pk_bf16_f32 v104, v28, v29
	v_pk_mul_f32 v[28:29], v[188:189], v[130:131] op_sel_hi:[0,1]
	v_pk_mul_f32 v[28:29], v[28:29], v[30:31]
	v_mov_b32_e32 v63, v129
	v_cvt_pk_bf16_f32 v105, v28, v29
	v_pk_mul_f32 v[28:29], v[188:189], v[106:107] op_sel_hi:[0,1]
	s_waitcnt lgkmcnt(2)
	v_pk_mul_f32 v[24:25], v[28:29], v[24:25]
	v_mov_b64_e32 v[32:33], v[48:49]
	v_cvt_pk_bf16_f32 v106, v24, v25
	v_pk_mul_f32 v[24:25], v[188:189], v[126:127] op_sel_hi:[0,1]
	v_pk_mul_f32 v[24:25], v[24:25], v[26:27]
	v_mul_u32_u24_e32 v169, 0x110, v186
	v_cvt_pk_bf16_f32 v107, v24, v25
	v_pk_mul_f32 v[24:25], v[188:189], v[108:109] op_sel_hi:[0,1]
	s_waitcnt lgkmcnt(1)
	v_pk_mul_f32 v[20:21], v[24:25], v[20:21]
	v_mov_b32_e32 v155, v158
	v_cvt_pk_bf16_f32 v108, v20, v21
	v_pk_mul_f32 v[20:21], v[188:189], v[124:125] op_sel_hi:[0,1]
	v_pk_mul_f32 v[20:21], v[20:21], v[22:23]
	v_lshl_add_u64 v[164:165], v[116:117], 2, s[4:5]
	v_cvt_pk_bf16_f32 v109, v20, v21
	v_pk_mul_f32 v[20:21], v[188:189], v[110:111] op_sel_hi:[0,1]
	s_waitcnt lgkmcnt(0)
	v_pk_mul_f32 v[16:17], v[20:21], v[16:17]
	v_add_u32_e32 v20, 0, v128
	v_cvt_pk_bf16_f32 v110, v16, v17
	v_pk_mul_f32 v[16:17], v[188:189], v[122:123] op_sel_hi:[0,1]
	v_pk_mul_f32 v[16:17], v[16:17], v[18:19]
	v_and_b32_e32 v19, 16, v154
	v_cvt_pk_bf16_f32 v111, v16, v17
	v_lshlrev_b32_e32 v16, 16, v12
	v_and_b32_e32 v17, 0xffff0000, v12
	v_pk_mul_f32 v[16:17], v[120:121], v[16:17] op_sel_hi:[0,1]
	v_cvt_pk_bf16_f32 v12, v16, v17
	v_lshlrev_b32_e32 v16, 16, v13
	v_and_b32_e32 v17, 0xffff0000, v13
	v_pk_mul_f32 v[16:17], v[120:121], v[16:17] op_sel_hi:[0,1]
	v_cvt_pk_bf16_f32 v13, v16, v17
	v_lshlrev_b32_e32 v16, 16, v14
	v_and_b32_e32 v17, 0xffff0000, v14
	v_pk_mul_f32 v[16:17], v[120:121], v[16:17] op_sel_hi:[0,1]
	v_cvt_pk_bf16_f32 v14, v16, v17
	v_lshlrev_b32_e32 v16, 16, v15
	v_and_b32_e32 v17, 0xffff0000, v15
	v_pk_mul_f32 v[16:17], v[120:121], v[16:17] op_sel_hi:[0,1]
	v_cvt_pk_bf16_f32 v15, v16, v17
	v_add_u32_e32 v16, v20, v174
	ds_write_b128 v16, v[12:15]
	ds_write_b128 v248, v[8:11] offset:17408
	v_lshlrev_b32_e32 v8, 16, v4
	v_and_b32_e32 v9, 0xffff0000, v4
	v_pk_mul_f32 v[8:9], v[118:119], v[8:9] op_sel_hi:[0,1]
	v_cvt_pk_bf16_f32 v4, v8, v9
	v_lshlrev_b32_e32 v8, 16, v5
	v_and_b32_e32 v9, 0xffff0000, v5
	v_pk_mul_f32 v[8:9], v[118:119], v[8:9] op_sel_hi:[0,1]
	v_cvt_pk_bf16_f32 v5, v8, v9
	v_lshlrev_b32_e32 v8, 16, v6
	v_and_b32_e32 v9, 0xffff0000, v6
	v_pk_mul_f32 v[8:9], v[118:119], v[8:9] op_sel_hi:[0,1]
	v_cvt_pk_bf16_f32 v6, v8, v9
	v_lshlrev_b32_e32 v8, 16, v7
	v_and_b32_e32 v9, 0xffff0000, v7
	v_pk_mul_f32 v[8:9], v[118:119], v[8:9] op_sel_hi:[0,1]
	v_cvt_pk_bf16_f32 v7, v8, v9
	v_add_u32_e32 v8, v20, v175
	ds_write_b128 v8, v[4:7]
	ds_write_b128 v248, v[0:3] offset:25600
	v_lshlrev_b32_e32 v1, 2, v185
	v_lshrrev_b32_e32 v18, 2, v154
	v_and_or_b32 v1, v1, 12, v19
	v_and_or_b32 v0, v18, 3, v159
	v_lshlrev_b32_e32 v177, 1, v1
	v_or_b32_e32 v1, 32, v185
	v_mul_u32_u24_e32 v176, 0x110, v1
	v_mul_u32_u24_e32 v188, 0x110, v0
	v_mov_b64_e32 v[16:17], v[48:49]
	v_mov_b64_e32 v[0:1], v[48:49]
	s_and_b32 s12, s58, 0xfc0
	v_subrev_u32_e32 v189, 64, v189
	v_subrev_u32_e32 v190, 64, v119
	v_mov_b32_e32 v167, 0
	v_mov_b32_e32 v192, 0xff800000
	v_mov_b64_e32 v[34:35], v[50:51]
	v_mov_b64_e32 v[36:37], v[52:53]
	v_mov_b64_e32 v[38:39], v[54:55]
	v_mov_b64_e32 v[40:41], v[56:57]
	v_mov_b64_e32 v[42:43], v[58:59]
	v_mov_b64_e32 v[44:45], v[60:61]
	v_mov_b64_e32 v[46:47], v[62:63]
	v_mov_b64_e32 v[18:19], v[50:51]
	v_mov_b64_e32 v[20:21], v[52:53]
	v_mov_b64_e32 v[22:23], v[54:55]
	v_mov_b64_e32 v[24:25], v[56:57]
	v_mov_b64_e32 v[26:27], v[58:59]
	v_mov_b64_e32 v[28:29], v[60:61]
	v_mov_b64_e32 v[30:31], v[62:63]
	v_mov_b64_e32 v[2:3], v[50:51]
	v_mov_b64_e32 v[4:5], v[52:53]
	v_mov_b64_e32 v[6:7], v[54:55]
	v_mov_b64_e32 v[8:9], v[56:57]
	v_mov_b64_e32 v[10:11], v[58:59]
	v_mov_b64_e32 v[12:13], v[60:61]
	v_mov_b64_e32 v[14:15], v[62:63]
	v_lshl_add_u64 v[138:139], s[12:13], 2, v[164:165]
	v_add_u32_e32 v65, s12, v190
	v_mov_b32_e32 v140, s33
	v_cmp_lt_i32_e32 vcc, 15, v65
	v_min_i32_e32 v64, 0x80f, v65
	s_nop 0
	v_cndmask_b32_e32 v65, v179, v140, vcc
	v_add_u32_e32 v66, v65, v64
	v_ashrrev_i32_e32 v67, 31, v66
	v_lshlrev_b64 v[66:67], 14, v[66:67]
	v_lshl_add_u64 v[66:67], v[160:161], 0, v[66:67]
	v_add_co_u32_e32 v72, vcc, s65, v66
	v_ashrrev_i32_e32 v65, 31, v64
	s_nop 0
	v_addc_co_u32_e32 v73, vcc, 0, v67, vcc
	v_add_co_u32_e32 v74, vcc, s63, v66
	v_lshl_add_u64 v[134:135], v[64:65], 2, s[54:55]
	s_nop 0
	v_addc_co_u32_e32 v75, vcc, 0, v67, vcc
	v_add_u32_e32 v67, s12, v189
	v_cmp_lt_i32_e32 vcc, 15, v67
	v_min_i32_e32 v66, 0x80f, v67
	s_nop 0
	v_cndmask_b32_e32 v67, v179, v140, vcc
	v_add_u32_e32 v68, v67, v66
	v_ashrrev_i32_e32 v69, 31, v68
	v_lshlrev_b64 v[68:69], 14, v[68:69]
	v_lshl_add_u64 v[68:69], v[160:161], 0, v[68:69]
	v_add_co_u32_e32 v76, vcc, 0x2000, v68
	v_ashrrev_i32_e32 v67, 31, v66
	s_nop 0
	v_addc_co_u32_e32 v77, vcc, 0, v69, vcc
	v_add_co_u32_e32 v78, vcc, 0x3000, v68
	v_lshl_add_u64 v[136:137], v[66:67], 2, s[54:55]
	s_nop 0
	v_addc_co_u32_e32 v79, vcc, 0, v69, vcc
	s_and_saveexec_b64 s[4:5], s[0:1]
	s_cbranch_execz .Llde_p
	global_load_dwordx4 v[112:115], v[138:139], off offset:-256
.Llde_p:
	s_or_b64 exec, exec, s[4:5]
	global_load_dwordx4 v[130:133], v[72:73], off offset:2048
	global_load_dwordx4 v[116:119], v[74:75], off
	global_load_dword v168, v[134:135], off
	global_load_dwordx4 v[120:123], v[76:77], off offset:2048
	global_load_dwordx4 v[124:127], v[78:79], off
	global_load_dword v166, v[136:137], off
	s_waitcnt lgkmcnt(0)
	s_barrier
	s_branch .LBB0_507
.LBB0_506:
	s_or_b64 exec, exec, s[4:5]
	s_sub_i32 s12, s12, 64
	s_add_i32 s64, s64, 1
	v_lshl_add_u64 v[138:139], s[12:13], 2, v[164:165]
	v_add_u32_e32 v65, s12, v190
	v_mov_b32_e32 v140, s33
	v_cmp_lt_i32_e32 vcc, 15, v65
	v_min_i32_e32 v64, 0x80f, v65
	s_nop 0
	v_cndmask_b32_e32 v65, v179, v140, vcc
	v_add_u32_e32 v66, v65, v64
	v_ashrrev_i32_e32 v67, 31, v66
	v_lshlrev_b64 v[66:67], 14, v[66:67]
	v_lshl_add_u64 v[66:67], v[160:161], 0, v[66:67]
	v_add_co_u32_e32 v72, vcc, s65, v66
	v_ashrrev_i32_e32 v65, 31, v64
	s_nop 0
	v_addc_co_u32_e32 v73, vcc, 0, v67, vcc
	v_add_co_u32_e32 v74, vcc, s63, v66
	v_lshl_add_u64 v[134:135], v[64:65], 2, s[54:55]
	s_nop 0
	v_addc_co_u32_e32 v75, vcc, 0, v67, vcc
	v_add_u32_e32 v67, s12, v189
	v_cmp_lt_i32_e32 vcc, 15, v67
	v_min_i32_e32 v66, 0x80f, v67
	s_nop 0
	v_cndmask_b32_e32 v67, v179, v140, vcc
	v_add_u32_e32 v68, v67, v66
	v_ashrrev_i32_e32 v69, 31, v68
	v_lshlrev_b64 v[68:69], 14, v[68:69]
	v_lshl_add_u64 v[68:69], v[160:161], 0, v[68:69]
	v_add_co_u32_e32 v76, vcc, 0x2000, v68
	v_ashrrev_i32_e32 v67, 31, v66
	s_nop 0
	v_addc_co_u32_e32 v77, vcc, 0, v69, vcc
	v_add_co_u32_e32 v78, vcc, 0x3000, v68
	v_lshl_add_u64 v[136:137], v[66:67], 2, s[54:55]
	s_nop 0
	v_addc_co_u32_e32 v79, vcc, 0, v69, vcc
	s_waitcnt vmcnt(5)
	v_lshlrev_b32_e32 v64, 16, v130
	v_and_b32_e32 v65, 0xffff0000, v130
	v_lshlrev_b32_e32 v66, 16, v131
	v_and_b32_e32 v67, 0xffff0000, v131
	s_waitcnt vmcnt(3)
	v_pk_mul_f32 v[64:65], v[168:169], v[64:65] op_sel_hi:[0,1]
	v_pk_mul_f32 v[66:67], v[168:169], v[66:67] op_sel_hi:[0,1]
	v_cvt_pk_bf16_f32 v64, v64, v65
	v_cvt_pk_bf16_f32 v65, v66, v67
	v_lshlrev_b32_e32 v66, 16, v132
	v_and_b32_e32 v67, 0xffff0000, v132
	v_lshlrev_b32_e32 v68, 16, v133
	v_and_b32_e32 v69, 0xffff0000, v133
	v_add_u32_e32 v70, s56, v128
	v_pk_mul_f32 v[66:67], v[168:169], v[66:67] op_sel_hi:[0,1]
	v_pk_mul_f32 v[68:69], v[168:169], v[68:69] op_sel_hi:[0,1]
	v_cvt_pk_bf16_f32 v66, v66, v67
	v_cvt_pk_bf16_f32 v67, v68, v69
	v_add_u32_e32 v68, v70, v174
	ds_write_b128 v68, v[64:67]
	v_add_u32_e32 v71, s56, v248
	ds_write_b128 v71, v[116:119] offset:17408
	s_waitcnt vmcnt(2)
	v_lshlrev_b32_e32 v64, 16, v120
	v_and_b32_e32 v65, 0xffff0000, v120
	v_lshlrev_b32_e32 v66, 16, v121
	v_and_b32_e32 v67, 0xffff0000, v121
	s_waitcnt vmcnt(0)
	v_pk_mul_f32 v[64:65], v[166:167], v[64:65] op_sel_hi:[0,1]
	v_pk_mul_f32 v[66:67], v[166:167], v[66:67] op_sel_hi:[0,1]
	v_cvt_pk_bf16_f32 v64, v64, v65
	v_cvt_pk_bf16_f32 v65, v66, v67
	v_lshlrev_b32_e32 v66, 16, v122
	v_and_b32_e32 v67, 0xffff0000, v122
	v_lshlrev_b32_e32 v68, 16, v123
	v_and_b32_e32 v69, 0xffff0000, v123
	v_pk_mul_f32 v[66:67], v[166:167], v[66:67] op_sel_hi:[0,1]
	v_pk_mul_f32 v[68:69], v[166:167], v[68:69] op_sel_hi:[0,1]
	v_cvt_pk_bf16_f32 v66, v66, v67
	v_cvt_pk_bf16_f32 v67, v68, v69
	v_add_u32_e32 v68, v70, v175
	s_cmp_eq_u32 s12, 0
	ds_write_b128 v68, v[64:67]
	ds_write_b128 v71, v[124:127] offset:25600
	s_cbranch_scc1 .Lld_skip
	s_and_saveexec_b64 s[4:5], s[0:1]
	s_cbranch_execz .Llde_b
	global_load_dwordx4 v[112:115], v[138:139], off offset:-256
.Llde_b:
	s_or_b64 exec, exec, s[4:5]
	global_load_dwordx4 v[130:133], v[72:73], off offset:2048
	global_load_dwordx4 v[116:119], v[74:75], off
	global_load_dword v168, v[134:135], off
	global_load_dwordx4 v[120:123], v[76:77], off offset:2048
	global_load_dwordx4 v[124:127], v[78:79], off
	global_load_dword v166, v[136:137], off
